# EpiRes epilogues (Wout and Wdown residual) rewritten with an 8-deep load pipeline and counted vmcnt instead of load-wait-store serialisation
# speedup vs baseline: 1.0012x; 1.0012x over previous
.LBB0_693:
	s_lshl_b32 s5, s12, 8
	s_cmp_lt_i32 s12, 64
	v_readlane_b32 s14, v253, 46
	v_readlane_b32 s15, v253, 47
	v_readlane_b32 s16, v254, 47
	v_readlane_b32 s36, v251, 4
	s_movk_i32 s7, 0x1800
	s_cselect_b32 s18, s14, s15
	v_readlane_b32 s15, v254, 56
	v_readlane_b32 s17, v254, 48
	v_readlane_b32 s14, v254, 55
	v_readlane_b32 s48, v251, 16
	v_readlane_b32 s49, v251, 17
	s_cselect_b32 s7, s7, 0x3000
	s_cselect_b32 s17, s17, s15
	s_cselect_b32 s16, s16, s14
	s_cselect_b32 s14, s48, s14
	s_cselect_b32 s15, s49, s15
	s_add_i32 s5, s18, s5
	s_lshl_b32 s18, s34, 8
	v_readlane_b32 s19, v253, 44
	v_mbcnt_lo_u32_b32 v128, -1, 0
	v_mbcnt_hi_u32_b32 v128, -1, v128
	s_or_b32 s18, s18, s19
	v_and_b32_e32 v132, 15, v128
	v_ashrrev_i32_e32 v128, 4, v128
	s_cmp_gt_i32 s12, 31
	s_cselect_b32 s7, s7, 0
	s_lshl_b32 s7, s7, 2
	v_add_u32_e32 v132, s5, v132
	v_lshl_add_u32 v128, v128, 2, s18
	s_add_u32 s18, s27, s7
	v_ashrrev_i32_e32 v133, 31, v132
	s_addc_u32 s19, s28, 0
	v_ashrrev_i32_e32 v129, 31, v128
	v_lshlrev_b64 v[132:133], 10, v[132:133]
	v_lshl_add_u64 v[130:131], v[128:129], 2, s[18:19]
	v_lshl_add_u64 v[128:129], v[132:133], 0, v[128:129]
	v_lshlrev_b64 v[150:151], 2, v[128:129]
	v_lshl_add_u64 v[158:159], s[16:17], 0, v[150:151]
	global_load_dwordx4 v[136:139], v[130:131], off
	global_load_dwordx4 v[140:143], v[130:131], off offset:64
	global_load_dwordx4 v[132:135], v[130:131], off offset:512
	s_nop 0
	global_load_dwordx4 v[128:131], v[130:131], off offset:576
	v_lshl_add_u64 v[162:163], s[14:15], 0, v[150:151]
	global_load_dwordx4 v[164:167], v[158:159], off
	global_load_dwordx4 v[168:171], v[158:159], off offset:64
	global_load_dwordx4 v[172:175], v[158:159], off offset:512
	global_load_dwordx4 v[176:179], v[158:159], off offset:576
	s_mov_b64 s[18:19], 0x10000
	v_lshl_add_u64 v[154:155], v[158:159], 0, s[18:19]
	global_load_dwordx4 v[180:183], v[154:155], off
	global_load_dwordx4 v[184:187], v[154:155], off offset:64
	global_load_dwordx4 v[188:191], v[154:155], off offset:512
	global_load_dwordx4 v[192:195], v[154:155], off offset:576
	s_andn2_b64 vcc, exec, s[0:1]
	s_mov_b64 s[0:1], -1
	v_readlane_b32 s37, v251, 5
	v_readlane_b32 s38, v251, 6
	v_readlane_b32 s39, v251, 7
	v_readlane_b32 s40, v251, 8
	v_readlane_b32 s41, v251, 9
	v_readlane_b32 s42, v251, 10
	v_readlane_b32 s43, v251, 11
	v_readlane_b32 s44, v251, 12
	v_readlane_b32 s45, v251, 13
	v_readlane_b32 s46, v251, 14
	v_readlane_b32 s47, v251, 15
	v_readlane_b32 s50, v251, 18
	v_readlane_b32 s51, v251, 19
	s_mov_b64 s[18:19], 0x20000
	v_lshl_add_u64 v[154:155], v[158:159], 0, s[18:19]
	s_waitcnt vmcnt(7)
	v_pk_fma_f32 v[126:127], v[126:127], v[138:139], v[166:167]
	v_pk_fma_f32 v[124:125], v[124:125], v[136:137], v[164:165]
	global_store_dwordx4 v[162:163], v[124:127], off
	global_load_dwordx4 v[164:167], v[154:155], off
	s_waitcnt vmcnt(8)
	v_pk_fma_f32 v[122:123], v[122:123], v[142:143], v[170:171]
	v_pk_fma_f32 v[120:121], v[120:121], v[140:141], v[168:169]
	global_store_dwordx4 v[162:163], v[120:123], off offset:64
	global_load_dwordx4 v[168:171], v[154:155], off offset:64
	s_waitcnt vmcnt(9)
	v_pk_fma_f32 v[118:119], v[118:119], v[134:135], v[174:175]
	v_pk_fma_f32 v[116:117], v[116:117], v[132:133], v[172:173]
	global_store_dwordx4 v[162:163], v[116:119], off offset:512
	global_load_dwordx4 v[172:175], v[154:155], off offset:512
	s_waitcnt vmcnt(10)
	v_pk_fma_f32 v[106:107], v[106:107], v[130:131], v[178:179]
	v_pk_fma_f32 v[104:105], v[104:105], v[128:129], v[176:177]
	global_store_dwordx4 v[162:163], v[104:107], off offset:576
	global_load_dwordx4 v[176:179], v[154:155], off offset:576
	s_mov_b64 s[18:19], 0x30000
	v_lshl_add_u64 v[154:155], v[158:159], 0, s[18:19]
	s_mov_b64 s[18:19], 0x10000
	v_lshl_add_u64 v[156:157], v[162:163], 0, s[18:19]
	s_waitcnt vmcnt(11)
	v_pk_fma_f32 v[114:115], v[114:115], v[138:139], v[182:183]
	v_pk_fma_f32 v[112:113], v[112:113], v[136:137], v[180:181]
	global_store_dwordx4 v[156:157], v[112:115], off
	global_load_dwordx4 v[180:183], v[154:155], off
	s_waitcnt vmcnt(12)
	v_pk_fma_f32 v[110:111], v[110:111], v[142:143], v[186:187]
	v_pk_fma_f32 v[108:109], v[108:109], v[140:141], v[184:185]
	global_store_dwordx4 v[156:157], v[108:111], off offset:64
	global_load_dwordx4 v[184:187], v[154:155], off offset:64
	s_waitcnt vmcnt(13)
	v_pk_fma_f32 v[102:103], v[102:103], v[134:135], v[190:191]
	v_pk_fma_f32 v[100:101], v[100:101], v[132:133], v[188:189]
	global_store_dwordx4 v[156:157], v[100:103], off offset:512
	global_load_dwordx4 v[188:191], v[154:155], off offset:512
	s_waitcnt vmcnt(14)
	v_pk_fma_f32 v[90:91], v[90:91], v[130:131], v[194:195]
	v_pk_fma_f32 v[88:89], v[88:89], v[128:129], v[192:193]
	global_store_dwordx4 v[156:157], v[88:91], off offset:576
	global_load_dwordx4 v[192:195], v[154:155], off offset:576
	s_mov_b64 s[18:19], 0x80000
	v_lshl_add_u64 v[154:155], v[158:159], 0, s[18:19]
	s_mov_b64 s[18:19], 0x20000
	v_lshl_add_u64 v[156:157], v[162:163], 0, s[18:19]
	s_waitcnt vmcnt(14)
	v_pk_fma_f32 v[98:99], v[98:99], v[138:139], v[166:167]
	v_pk_fma_f32 v[96:97], v[96:97], v[136:137], v[164:165]
	global_store_dwordx4 v[156:157], v[96:99], off
	global_load_dwordx4 v[164:167], v[154:155], off
	s_waitcnt vmcnt(14)
	v_pk_fma_f32 v[94:95], v[94:95], v[142:143], v[170:171]
	v_pk_fma_f32 v[92:93], v[92:93], v[140:141], v[168:169]
	global_store_dwordx4 v[156:157], v[92:95], off offset:64
	global_load_dwordx4 v[168:171], v[154:155], off offset:64
	s_waitcnt vmcnt(14)
	v_pk_fma_f32 v[86:87], v[86:87], v[134:135], v[174:175]
	v_pk_fma_f32 v[84:85], v[84:85], v[132:133], v[172:173]
	global_store_dwordx4 v[156:157], v[84:87], off offset:512
	global_load_dwordx4 v[172:175], v[154:155], off offset:512
	s_waitcnt vmcnt(14)
	v_pk_fma_f32 v[74:75], v[74:75], v[130:131], v[178:179]
	v_pk_fma_f32 v[72:73], v[72:73], v[128:129], v[176:177]
	global_store_dwordx4 v[156:157], v[72:75], off offset:576
	global_load_dwordx4 v[176:179], v[154:155], off offset:576
	s_mov_b64 s[18:19], 0x90000
	v_lshl_add_u64 v[154:155], v[158:159], 0, s[18:19]
	s_mov_b64 s[18:19], 0x30000
	v_lshl_add_u64 v[156:157], v[162:163], 0, s[18:19]
	s_waitcnt vmcnt(14)
	v_pk_fma_f32 v[82:83], v[82:83], v[138:139], v[182:183]
	v_pk_fma_f32 v[80:81], v[80:81], v[136:137], v[180:181]
	global_store_dwordx4 v[156:157], v[80:83], off
	global_load_dwordx4 v[180:183], v[154:155], off
	s_waitcnt vmcnt(14)
	v_pk_fma_f32 v[78:79], v[78:79], v[142:143], v[186:187]
	v_pk_fma_f32 v[76:77], v[76:77], v[140:141], v[184:185]
	global_store_dwordx4 v[156:157], v[76:79], off offset:64
	global_load_dwordx4 v[184:187], v[154:155], off offset:64
	s_waitcnt vmcnt(14)
	v_pk_fma_f32 v[70:71], v[70:71], v[134:135], v[190:191]
	v_pk_fma_f32 v[68:69], v[68:69], v[132:133], v[188:189]
	global_store_dwordx4 v[156:157], v[68:71], off offset:512
	global_load_dwordx4 v[188:191], v[154:155], off offset:512
	s_waitcnt vmcnt(14)
	v_pk_fma_f32 v[66:67], v[66:67], v[130:131], v[194:195]
	v_pk_fma_f32 v[64:65], v[64:65], v[128:129], v[192:193]
	global_store_dwordx4 v[156:157], v[64:67], off offset:576
	global_load_dwordx4 v[192:195], v[154:155], off offset:576
	s_mov_b64 s[18:19], 0xa0000
	v_lshl_add_u64 v[154:155], v[158:159], 0, s[18:19]
	s_mov_b64 s[18:19], 0x80000
	v_lshl_add_u64 v[156:157], v[162:163], 0, s[18:19]
	s_waitcnt vmcnt(14)
	v_pk_fma_f32 v[62:63], v[62:63], v[138:139], v[166:167]
	v_pk_fma_f32 v[60:61], v[60:61], v[136:137], v[164:165]
	global_store_dwordx4 v[156:157], v[60:63], off
	global_load_dwordx4 v[164:167], v[154:155], off
	s_waitcnt vmcnt(14)
	v_pk_fma_f32 v[58:59], v[58:59], v[142:143], v[170:171]
	v_pk_fma_f32 v[56:57], v[56:57], v[140:141], v[168:169]
	global_store_dwordx4 v[156:157], v[56:59], off offset:64
	global_load_dwordx4 v[168:171], v[154:155], off offset:64
	s_waitcnt vmcnt(14)
	v_pk_fma_f32 v[54:55], v[54:55], v[134:135], v[174:175]
	v_pk_fma_f32 v[52:53], v[52:53], v[132:133], v[172:173]
	global_store_dwordx4 v[156:157], v[52:55], off offset:512
	global_load_dwordx4 v[172:175], v[154:155], off offset:512
	s_waitcnt vmcnt(14)
	v_pk_fma_f32 v[42:43], v[42:43], v[130:131], v[178:179]
	v_pk_fma_f32 v[40:41], v[40:41], v[128:129], v[176:177]
	global_store_dwordx4 v[156:157], v[40:43], off offset:576
	global_load_dwordx4 v[176:179], v[154:155], off offset:576
	s_mov_b64 s[18:19], 0xb0000
	v_lshl_add_u64 v[154:155], v[158:159], 0, s[18:19]
	s_mov_b64 s[18:19], 0x90000
	v_lshl_add_u64 v[156:157], v[162:163], 0, s[18:19]
	s_waitcnt vmcnt(14)
	v_pk_fma_f32 v[50:51], v[50:51], v[138:139], v[182:183]
	v_pk_fma_f32 v[48:49], v[48:49], v[136:137], v[180:181]
	global_store_dwordx4 v[156:157], v[48:51], off
	global_load_dwordx4 v[180:183], v[154:155], off
	s_waitcnt vmcnt(14)
	v_pk_fma_f32 v[46:47], v[46:47], v[142:143], v[186:187]
	v_pk_fma_f32 v[44:45], v[44:45], v[140:141], v[184:185]
	global_store_dwordx4 v[156:157], v[44:47], off offset:64
	global_load_dwordx4 v[184:187], v[154:155], off offset:64
	s_waitcnt vmcnt(14)
	v_pk_fma_f32 v[38:39], v[38:39], v[134:135], v[190:191]
	v_pk_fma_f32 v[36:37], v[36:37], v[132:133], v[188:189]
	global_store_dwordx4 v[156:157], v[36:39], off offset:512
	global_load_dwordx4 v[188:191], v[154:155], off offset:512
	s_waitcnt vmcnt(14)
	v_pk_fma_f32 v[26:27], v[26:27], v[130:131], v[194:195]
	v_pk_fma_f32 v[24:25], v[24:25], v[128:129], v[192:193]
	global_store_dwordx4 v[156:157], v[24:27], off offset:576
	global_load_dwordx4 v[192:195], v[154:155], off offset:576
	s_mov_b64 s[18:19], 0xa0000
	v_lshl_add_u64 v[156:157], v[162:163], 0, s[18:19]
	s_waitcnt vmcnt(14)
	v_pk_fma_f32 v[34:35], v[34:35], v[138:139], v[166:167]
	v_pk_fma_f32 v[32:33], v[32:33], v[136:137], v[164:165]
	global_store_dwordx4 v[156:157], v[32:35], off
	s_waitcnt vmcnt(13)
	v_pk_fma_f32 v[30:31], v[30:31], v[142:143], v[170:171]
	v_pk_fma_f32 v[28:29], v[28:29], v[140:141], v[168:169]
	global_store_dwordx4 v[156:157], v[28:31], off offset:64
	s_waitcnt vmcnt(12)
	v_pk_fma_f32 v[22:23], v[22:23], v[134:135], v[174:175]
	v_pk_fma_f32 v[20:21], v[20:21], v[132:133], v[172:173]
	global_store_dwordx4 v[156:157], v[20:23], off offset:512
	s_waitcnt vmcnt(11)
	v_pk_fma_f32 v[10:11], v[10:11], v[130:131], v[178:179]
	v_pk_fma_f32 v[8:9], v[8:9], v[128:129], v[176:177]
	global_store_dwordx4 v[156:157], v[8:11], off offset:576
	s_mov_b64 s[18:19], 0xb0000
	v_lshl_add_u64 v[156:157], v[162:163], 0, s[18:19]
	s_waitcnt vmcnt(10)
	v_pk_fma_f32 v[18:19], v[18:19], v[138:139], v[182:183]
	v_pk_fma_f32 v[16:17], v[16:17], v[136:137], v[180:181]
	global_store_dwordx4 v[156:157], v[16:19], off
	s_waitcnt vmcnt(9)
	v_pk_fma_f32 v[14:15], v[14:15], v[142:143], v[186:187]
	v_pk_fma_f32 v[12:13], v[12:13], v[140:141], v[184:185]
	global_store_dwordx4 v[156:157], v[12:15], off offset:64
	s_waitcnt vmcnt(8)
	v_pk_fma_f32 v[6:7], v[6:7], v[134:135], v[190:191]
	v_pk_fma_f32 v[4:5], v[4:5], v[132:133], v[188:189]
	global_store_dwordx4 v[156:157], v[4:7], off offset:512
	s_waitcnt vmcnt(7)
	v_pk_fma_f32 v[2:3], v[2:3], v[130:131], v[194:195]
	v_pk_fma_f32 v[0:1], v[0:1], v[128:129], v[192:193]
	global_store_dwordx4 v[156:157], v[0:3], off offset:576
	s_cbranch_vccnz .LBB0_686
	s_and_b64 vcc, exec, s[76:77]
	s_cbranch_vccnz .LBB0_685
	s_barrier
	s_branch .LBB0_685

.LBB0_939:
	s_lshl_b32 s8, s27, 8
	s_cmp_lt_i32 s27, 64
	s_movk_i32 s6, 0x1800
	s_cselect_b32 s9, s6, 0x3000
	v_readlane_b32 s6, v253, 46
	v_readlane_b32 s7, v253, 47
	v_readlane_b32 s40, v251, 4
	s_cselect_b32 s10, s6, s7
	v_readlane_b32 s52, v251, 16
	v_readlane_b32 s53, v251, 17
	v_readlane_b32 s6, v254, 55
	v_readlane_b32 s7, v254, 56
	v_mbcnt_lo_u32_b32 v76, -1, 0
	v_mbcnt_hi_u32_b32 v76, -1, v76
	s_cselect_b32 s6, s52, s6
	s_cselect_b32 s7, s53, s7
	s_add_i32 s10, s10, s8
	s_lshl_b32 s8, s28, 8
	v_readlane_b32 s11, v253, 44
	v_and_b32_e32 v154, 15, v76
	v_ashrrev_i32_e32 v76, 4, v76
	s_or_b32 s8, s8, s11
	s_cmp_gt_i32 s27, 31
	v_lshl_add_u32 v76, v76, 2, s8
	s_cselect_b32 s8, s9, 0
	v_add_u32_e32 v154, s10, v154
	s_lshl_b32 s8, s8, 2
	v_ashrrev_i32_e32 v155, 31, v154
	s_add_u32 s8, s20, s8
	v_ashrrev_i32_e32 v77, 31, v76
	v_lshlrev_b64 v[154:155], 12, v[154:155]
	s_addc_u32 s9, s21, 0
	v_lshlrev_b64 v[150:151], 2, v[76:77]
	v_lshl_add_u64 v[154:155], s[6:7], 0, v[154:155]
	v_lshl_add_u64 v[76:77], s[8:9], 0, v[150:151]
	v_lshl_add_u64 v[150:151], v[154:155], 0, v[150:151]
	global_load_dwordx4 v[92:95], v[76:77], off
	global_load_dwordx4 v[88:91], v[76:77], off offset:64
	global_load_dwordx4 v[84:87], v[76:77], off offset:512
	s_nop 0
	global_load_dwordx4 v[76:79], v[76:77], off offset:576
	global_load_dwordx4 v[164:167], v[150:151], off
	global_load_dwordx4 v[168:171], v[150:151], off offset:64
	global_load_dwordx4 v[172:175], v[150:151], off offset:512
	global_load_dwordx4 v[176:179], v[150:151], off offset:576
	s_mov_b64 s[6:7], 0x10000
	v_lshl_add_u64 v[154:155], v[150:151], 0, s[6:7]
	global_load_dwordx4 v[180:183], v[154:155], off
	global_load_dwordx4 v[184:187], v[154:155], off offset:64
	global_load_dwordx4 v[188:191], v[154:155], off offset:512
	global_load_dwordx4 v[192:195], v[154:155], off offset:576
	v_readlane_b32 s41, v251, 5
	v_readlane_b32 s42, v251, 6
	v_readlane_b32 s43, v251, 7
	v_readlane_b32 s44, v251, 8
	v_readlane_b32 s45, v251, 9
	v_readlane_b32 s46, v251, 10
	v_readlane_b32 s47, v251, 11
	v_readlane_b32 s48, v251, 12
	v_readlane_b32 s49, v251, 13
	v_readlane_b32 s50, v251, 14
	v_readlane_b32 s51, v251, 15
	v_readlane_b32 s54, v251, 18
	v_readlane_b32 s55, v251, 19
	s_mov_b64 s[6:7], 0x20000
	v_lshl_add_u64 v[154:155], v[150:151], 0, s[6:7]
	s_waitcnt vmcnt(7)
	v_pk_fma_f32 v[142:143], v[142:143], v[94:95], v[166:167]
	v_pk_fma_f32 v[140:141], v[140:141], v[92:93], v[164:165]
	global_store_dwordx4 v[150:151], v[140:143], off
	global_load_dwordx4 v[164:167], v[154:155], off
	s_waitcnt vmcnt(8)
	v_pk_fma_f32 v[138:139], v[138:139], v[90:91], v[170:171]
	v_pk_fma_f32 v[136:137], v[136:137], v[88:89], v[168:169]
	global_store_dwordx4 v[150:151], v[136:139], off offset:64
	global_load_dwordx4 v[168:171], v[154:155], off offset:64
	s_waitcnt vmcnt(9)
	v_pk_fma_f32 v[134:135], v[134:135], v[86:87], v[174:175]
	v_pk_fma_f32 v[132:133], v[132:133], v[84:85], v[172:173]
	global_store_dwordx4 v[150:151], v[132:135], off offset:512
	global_load_dwordx4 v[172:175], v[154:155], off offset:512
	s_waitcnt vmcnt(10)
	v_pk_fma_f32 v[126:127], v[126:127], v[78:79], v[178:179]
	v_pk_fma_f32 v[124:125], v[124:125], v[76:77], v[176:177]
	global_store_dwordx4 v[150:151], v[124:127], off offset:576
	global_load_dwordx4 v[176:179], v[154:155], off offset:576
	s_mov_b64 s[6:7], 0x30000
	v_lshl_add_u64 v[154:155], v[150:151], 0, s[6:7]
	s_mov_b64 s[6:7], 0x10000
	v_lshl_add_u64 v[156:157], v[150:151], 0, s[6:7]
	s_waitcnt vmcnt(11)
	v_pk_fma_f32 v[130:131], v[130:131], v[94:95], v[182:183]
	v_pk_fma_f32 v[128:129], v[128:129], v[92:93], v[180:181]
	global_store_dwordx4 v[156:157], v[128:131], off
	global_load_dwordx4 v[180:183], v[154:155], off
	s_waitcnt vmcnt(12)
	v_pk_fma_f32 v[122:123], v[122:123], v[90:91], v[186:187]
	v_pk_fma_f32 v[120:121], v[120:121], v[88:89], v[184:185]
	global_store_dwordx4 v[156:157], v[120:123], off offset:64
	global_load_dwordx4 v[184:187], v[154:155], off offset:64
	s_waitcnt vmcnt(13)
	v_pk_fma_f32 v[118:119], v[118:119], v[86:87], v[190:191]
	v_pk_fma_f32 v[116:117], v[116:117], v[84:85], v[188:189]
	global_store_dwordx4 v[156:157], v[116:119], off offset:512
	global_load_dwordx4 v[188:191], v[154:155], off offset:512
	s_waitcnt vmcnt(14)
	v_pk_fma_f32 v[114:115], v[114:115], v[78:79], v[194:195]
	v_pk_fma_f32 v[112:113], v[112:113], v[76:77], v[192:193]
	global_store_dwordx4 v[156:157], v[112:115], off offset:576
	global_load_dwordx4 v[192:195], v[154:155], off offset:576
	s_mov_b64 s[6:7], 0x80000
	v_lshl_add_u64 v[154:155], v[150:151], 0, s[6:7]
	s_mov_b64 s[6:7], 0x20000
	v_lshl_add_u64 v[156:157], v[150:151], 0, s[6:7]
	s_waitcnt vmcnt(14)
	v_pk_fma_f32 v[110:111], v[110:111], v[94:95], v[166:167]
	v_pk_fma_f32 v[108:109], v[108:109], v[92:93], v[164:165]
	global_store_dwordx4 v[156:157], v[108:111], off
	global_load_dwordx4 v[164:167], v[154:155], off
	s_waitcnt vmcnt(14)
	v_pk_fma_f32 v[106:107], v[106:107], v[90:91], v[170:171]
	v_pk_fma_f32 v[104:105], v[104:105], v[88:89], v[168:169]
	global_store_dwordx4 v[156:157], v[104:107], off offset:64
	global_load_dwordx4 v[168:171], v[154:155], off offset:64
	s_waitcnt vmcnt(14)
	v_pk_fma_f32 v[102:103], v[102:103], v[86:87], v[174:175]
	v_pk_fma_f32 v[100:101], v[100:101], v[84:85], v[172:173]
	global_store_dwordx4 v[156:157], v[100:103], off offset:512
	global_load_dwordx4 v[172:175], v[154:155], off offset:512
	s_waitcnt vmcnt(14)
	v_pk_fma_f32 v[98:99], v[98:99], v[78:79], v[178:179]
	v_pk_fma_f32 v[96:97], v[96:97], v[76:77], v[176:177]
	global_store_dwordx4 v[156:157], v[96:99], off offset:576
	global_load_dwordx4 v[176:179], v[154:155], off offset:576
	s_mov_b64 s[6:7], 0x90000
	v_lshl_add_u64 v[154:155], v[150:151], 0, s[6:7]
	s_mov_b64 s[6:7], 0x30000
	v_lshl_add_u64 v[156:157], v[150:151], 0, s[6:7]
	s_waitcnt vmcnt(14)
	v_pk_fma_f32 v[82:83], v[82:83], v[94:95], v[182:183]
	v_pk_fma_f32 v[80:81], v[80:81], v[92:93], v[180:181]
	global_store_dwordx4 v[156:157], v[80:83], off
	global_load_dwordx4 v[180:183], v[154:155], off
	s_waitcnt vmcnt(14)
	v_pk_fma_f32 v[74:75], v[74:75], v[90:91], v[186:187]
	v_pk_fma_f32 v[72:73], v[72:73], v[88:89], v[184:185]
	global_store_dwordx4 v[156:157], v[72:75], off offset:64
	global_load_dwordx4 v[184:187], v[154:155], off offset:64
	s_waitcnt vmcnt(14)
	v_pk_fma_f32 v[70:71], v[70:71], v[86:87], v[190:191]
	v_pk_fma_f32 v[68:69], v[68:69], v[84:85], v[188:189]
	global_store_dwordx4 v[156:157], v[68:71], off offset:512
	global_load_dwordx4 v[188:191], v[154:155], off offset:512
	s_waitcnt vmcnt(14)
	v_pk_fma_f32 v[66:67], v[66:67], v[78:79], v[194:195]
	v_pk_fma_f32 v[64:65], v[64:65], v[76:77], v[192:193]
	global_store_dwordx4 v[156:157], v[64:67], off offset:576
	global_load_dwordx4 v[192:195], v[154:155], off offset:576
	s_mov_b64 s[6:7], 0xa0000
	v_lshl_add_u64 v[154:155], v[150:151], 0, s[6:7]
	s_mov_b64 s[6:7], 0x80000
	v_lshl_add_u64 v[156:157], v[150:151], 0, s[6:7]
	s_waitcnt vmcnt(14)
	v_pk_fma_f32 v[62:63], v[62:63], v[94:95], v[166:167]
	v_pk_fma_f32 v[60:61], v[60:61], v[92:93], v[164:165]
	global_store_dwordx4 v[156:157], v[60:63], off
	global_load_dwordx4 v[164:167], v[154:155], off
	s_waitcnt vmcnt(14)
	v_pk_fma_f32 v[58:59], v[58:59], v[90:91], v[170:171]
	v_pk_fma_f32 v[56:57], v[56:57], v[88:89], v[168:169]
	global_store_dwordx4 v[156:157], v[56:59], off offset:64
	global_load_dwordx4 v[168:171], v[154:155], off offset:64
	s_waitcnt vmcnt(14)
	v_pk_fma_f32 v[54:55], v[54:55], v[86:87], v[174:175]
	v_pk_fma_f32 v[52:53], v[52:53], v[84:85], v[172:173]
	global_store_dwordx4 v[156:157], v[52:55], off offset:512
	global_load_dwordx4 v[172:175], v[154:155], off offset:512
	s_waitcnt vmcnt(14)
	v_pk_fma_f32 v[50:51], v[50:51], v[78:79], v[178:179]
	v_pk_fma_f32 v[48:49], v[48:49], v[76:77], v[176:177]
	global_store_dwordx4 v[156:157], v[48:51], off offset:576
	global_load_dwordx4 v[176:179], v[154:155], off offset:576
	s_mov_b64 s[6:7], 0xb0000
	v_lshl_add_u64 v[154:155], v[150:151], 0, s[6:7]
	s_mov_b64 s[6:7], 0x90000
	v_lshl_add_u64 v[156:157], v[150:151], 0, s[6:7]
	s_waitcnt vmcnt(14)
	v_pk_fma_f32 v[46:47], v[46:47], v[94:95], v[182:183]
	v_pk_fma_f32 v[44:45], v[44:45], v[92:93], v[180:181]
	global_store_dwordx4 v[156:157], v[44:47], off
	global_load_dwordx4 v[180:183], v[154:155], off
	s_waitcnt vmcnt(14)
	v_pk_fma_f32 v[42:43], v[42:43], v[90:91], v[186:187]
	v_pk_fma_f32 v[40:41], v[40:41], v[88:89], v[184:185]
	global_store_dwordx4 v[156:157], v[40:43], off offset:64
	global_load_dwordx4 v[184:187], v[154:155], off offset:64
	s_waitcnt vmcnt(14)
	v_pk_fma_f32 v[38:39], v[38:39], v[86:87], v[190:191]
	v_pk_fma_f32 v[36:37], v[36:37], v[84:85], v[188:189]
	global_store_dwordx4 v[156:157], v[36:39], off offset:512
	global_load_dwordx4 v[188:191], v[154:155], off offset:512
	s_waitcnt vmcnt(14)
	v_pk_fma_f32 v[34:35], v[34:35], v[78:79], v[194:195]
	v_pk_fma_f32 v[32:33], v[32:33], v[76:77], v[192:193]
	global_store_dwordx4 v[156:157], v[32:35], off offset:576
	global_load_dwordx4 v[192:195], v[154:155], off offset:576
	s_mov_b64 s[6:7], 0xa0000
	v_lshl_add_u64 v[156:157], v[150:151], 0, s[6:7]
	s_waitcnt vmcnt(14)
	v_pk_fma_f32 v[30:31], v[30:31], v[94:95], v[166:167]
	v_pk_fma_f32 v[28:29], v[28:29], v[92:93], v[164:165]
	global_store_dwordx4 v[156:157], v[28:31], off
	s_waitcnt vmcnt(13)
	v_pk_fma_f32 v[26:27], v[26:27], v[90:91], v[170:171]
	v_pk_fma_f32 v[24:25], v[24:25], v[88:89], v[168:169]
	global_store_dwordx4 v[156:157], v[24:27], off offset:64
	s_waitcnt vmcnt(12)
	v_pk_fma_f32 v[22:23], v[22:23], v[86:87], v[174:175]
	v_pk_fma_f32 v[20:21], v[20:21], v[84:85], v[172:173]
	global_store_dwordx4 v[156:157], v[20:23], off offset:512
	s_waitcnt vmcnt(11)
	v_pk_fma_f32 v[18:19], v[18:19], v[78:79], v[178:179]
	v_pk_fma_f32 v[16:17], v[16:17], v[76:77], v[176:177]
	global_store_dwordx4 v[156:157], v[16:19], off offset:576
	s_mov_b64 s[6:7], 0xb0000
	v_lshl_add_u64 v[156:157], v[150:151], 0, s[6:7]
	s_waitcnt vmcnt(10)
	v_pk_fma_f32 v[14:15], v[14:15], v[94:95], v[182:183]
	v_pk_fma_f32 v[12:13], v[12:13], v[92:93], v[180:181]
	global_store_dwordx4 v[156:157], v[12:15], off
	s_waitcnt vmcnt(9)
	v_pk_fma_f32 v[10:11], v[10:11], v[90:91], v[186:187]
	v_pk_fma_f32 v[8:9], v[8:9], v[88:89], v[184:185]
	global_store_dwordx4 v[156:157], v[8:11], off offset:64
	s_waitcnt vmcnt(8)
	v_pk_fma_f32 v[6:7], v[6:7], v[86:87], v[190:191]
	v_pk_fma_f32 v[4:5], v[4:5], v[84:85], v[188:189]
	global_store_dwordx4 v[156:157], v[4:7], off offset:512
	s_waitcnt vmcnt(7)
	v_pk_fma_f32 v[2:3], v[2:3], v[78:79], v[194:195]
	v_pk_fma_f32 v[0:1], v[0:1], v[76:77], v[192:193]
	global_store_dwordx4 v[156:157], v[0:3], off offset:576
	s_mov_b64 s[6:7], -1
	s_and_b64 vcc, exec, s[38:39]
	s_cbranch_vccnz .LBB0_928
	s_and_b64 vcc, exec, s[76:77]
	s_cbranch_vccnz .LBB0_927
	s_barrier
	s_branch .LBB0_927
